# v39: v37 + the eight GEMM K-loop headers aligned to 64-byte fetch lines
# speedup vs baseline: 1.0091x; 1.0091x over previous
;     DI bool next(int i, Unit& u) const { const int L = (i / 3) * G + c; if (L >= 512) return false; pg8::swz_tile(L, 128, 4, u.pm, u.pn); u.k = i % 3; return true; }
;     DI bool next(int i, Unit& u) const { if (i >= 3) return false; u.pm = pm; u.pn = pn; u.k = i; return true; }
;     DI bool next(int i, Unit& u) const { if (i >= 1) return false; u.pm = pm; u.pn = pn; u.k = 0; return true; }
;     DI bool next(int i, Unit& u) const { if (i >= 1) return false; u.pm = pm; u.pn = pn; u.k = half; return true; }
;     DI bool next(int i, Unit& u) const { const int L = i * G + c; if (L >= nM * nN) return false; pg8::swz_tile(L, nM, nN, u.pm, u.pn); u.k = 0; return true; }
; template <class Epi, class Sched>
; DI void gemm_phase(LAS unsigned char* lds, const Sched& S, const Epi& E) {
;     ...
;         const bool has_next = S.next(ui + 1, nxt);
;         const char* nA = has_next ? S.pa(nxt) : cA; const char* nB = has_next ? S.pb(nxt) : cB;
;     ...
; #pragma unroll
;         for (int a = 0; a < 2; ++a)
; #pragma unroll
;             for (int b = 0; b < 2; ++b)
; #pragma unroll
;                 for (int m = 0; m < 4; ++m)
; #pragma unroll
;                     for (int n = 0; n < 2; ++n) acc[a][b][m][n] = (f32x4){0.f, 0.f, 0.f, 0.f};
;         cur = nxt; cA = nA; cB = nB; ++ui;
.LBB0_114:
	s_ashr_i32 s89, s88, 31
	s_lshl_b64 s[8:9], s[88:89], 19
	s_add_u32 s90, s62, s8
	s_addc_u32 s91, s63, s9
	s_and_b64 s[8:9], s[84:85], exec
	s_cselect_b32 s10, s91, s5
	s_cselect_b32 s11, s90, s4
	s_ashr_i32 s87, s86, 31
	s_lshl_b64 s[8:9], s[86:87], 19
	s_add_u32 s92, s42, s8
	s_addc_u32 s93, s43, s9
	s_and_b64 s[8:9], s[84:85], exec
	s_waitcnt lgkmcnt(0)
	s_cselect_b32 s16, s93, s7
	s_cselect_b32 s17, s92, s6
	s_add_u32 s4, s4, 0x40080
	s_addc_u32 s5, s5, 0
	s_add_u32 s18, s6, 0x100
	v_mov_b32_e32 v2, 0
	s_addc_u32 s19, s7, 0
	s_mov_b32 s28, -2
	v_mov_b32_e32 v3, v2
	v_mov_b32_e32 v4, v2
	v_mov_b32_e32 v5, v2
	v_mov_b32_e32 v6, v2
	v_mov_b32_e32 v7, v2
	v_mov_b32_e32 v8, v2
	v_mov_b32_e32 v9, v2
	v_mov_b32_e32 v18, v2
	v_mov_b32_e32 v19, v2
	v_mov_b32_e32 v20, v2
	v_mov_b32_e32 v21, v2
	v_mov_b32_e32 v22, v2
	v_mov_b32_e32 v23, v2
	v_mov_b32_e32 v24, v2
	v_mov_b32_e32 v25, v2
	v_mov_b32_e32 v34, v2
	v_mov_b32_e32 v35, v2
	v_mov_b32_e32 v36, v2
	v_mov_b32_e32 v37, v2
	v_mov_b32_e32 v38, v2
	v_mov_b32_e32 v39, v2
	v_mov_b32_e32 v40, v2
	v_mov_b32_e32 v41, v2
	v_mov_b32_e32 v50, v2
	v_mov_b32_e32 v51, v2
	v_mov_b32_e32 v52, v2
	v_mov_b32_e32 v53, v2
	v_mov_b32_e32 v54, v2
	v_mov_b32_e32 v55, v2
	v_mov_b32_e32 v56, v2
	v_mov_b32_e32 v57, v2
	v_mov_b32_e32 v10, v2
	v_mov_b32_e32 v11, v2
	v_mov_b32_e32 v12, v2
	v_mov_b32_e32 v13, v2
	v_mov_b32_e32 v14, v2
	v_mov_b32_e32 v15, v2
	v_mov_b32_e32 v16, v2
	v_mov_b32_e32 v17, v2
	v_mov_b32_e32 v26, v2
	v_mov_b32_e32 v27, v2
	v_mov_b32_e32 v28, v2
	v_mov_b32_e32 v29, v2
	v_mov_b32_e32 v30, v2
	v_mov_b32_e32 v31, v2
	v_mov_b32_e32 v32, v2
	v_mov_b32_e32 v33, v2
	v_mov_b32_e32 v42, v2
	v_mov_b32_e32 v43, v2
	v_mov_b32_e32 v44, v2
	v_mov_b32_e32 v45, v2
	v_mov_b32_e32 v46, v2
	v_mov_b32_e32 v47, v2
	v_mov_b32_e32 v48, v2
	v_mov_b32_e32 v49, v2
	v_mov_b32_e32 v58, v2
	v_mov_b32_e32 v59, v2
	v_mov_b32_e32 v60, v2
	v_mov_b32_e32 v61, v2
	v_mov_b32_e32 v62, v2
	v_mov_b32_e32 v63, v2
	v_mov_b32_e32 v64, v2
	v_mov_b32_e32 v65, v2
	v_mov_b32_e32 v66, v2
	v_mov_b32_e32 v67, v2
	v_mov_b32_e32 v68, v2
	v_mov_b32_e32 v69, v2
	v_mov_b32_e32 v70, v2
	v_mov_b32_e32 v71, v2
	v_mov_b32_e32 v72, v2
	v_mov_b32_e32 v73, v2
	v_mov_b32_e32 v82, v2
	v_mov_b32_e32 v83, v2
	v_mov_b32_e32 v84, v2
	v_mov_b32_e32 v85, v2
	v_mov_b32_e32 v86, v2
	v_mov_b32_e32 v87, v2
	v_mov_b32_e32 v88, v2
	v_mov_b32_e32 v89, v2
	v_mov_b32_e32 v98, v2
	v_mov_b32_e32 v99, v2
	v_mov_b32_e32 v100, v2
	v_mov_b32_e32 v101, v2
	v_mov_b32_e32 v102, v2
	v_mov_b32_e32 v103, v2
	v_mov_b32_e32 v104, v2
	v_mov_b32_e32 v105, v2
	v_mov_b32_e32 v114, v2
	v_mov_b32_e32 v115, v2
	v_mov_b32_e32 v116, v2
	v_mov_b32_e32 v117, v2
	v_mov_b32_e32 v118, v2
	v_mov_b32_e32 v119, v2
	v_mov_b32_e32 v120, v2
	v_mov_b32_e32 v121, v2
	v_mov_b32_e32 v74, v2
	v_mov_b32_e32 v75, v2
	v_mov_b32_e32 v76, v2
	v_mov_b32_e32 v77, v2
	v_mov_b32_e32 v78, v2
	v_mov_b32_e32 v79, v2
	v_mov_b32_e32 v80, v2
	v_mov_b32_e32 v81, v2
	v_mov_b32_e32 v90, v2
	v_mov_b32_e32 v91, v2
	v_mov_b32_e32 v92, v2
	v_mov_b32_e32 v93, v2
	v_mov_b32_e32 v94, v2
	v_mov_b32_e32 v95, v2
	v_mov_b32_e32 v96, v2
	v_mov_b32_e32 v97, v2
	v_mov_b32_e32 v106, v2
	v_mov_b32_e32 v107, v2
	v_mov_b32_e32 v108, v2
	v_mov_b32_e32 v109, v2
	v_mov_b32_e32 v110, v2
	v_mov_b32_e32 v111, v2
	v_mov_b32_e32 v112, v2
	v_mov_b32_e32 v113, v2
	v_mov_b32_e32 v122, v2
	v_mov_b32_e32 v123, v2
	v_mov_b32_e32 v124, v2
	v_mov_b32_e32 v125, v2
	v_mov_b32_e32 v126, v2
	v_mov_b32_e32 v127, v2
	v_mov_b32_e32 v128, v2
	v_mov_b32_e32 v129, v2
	.p2align	6

;     DI bool next(int i, Unit& u) const { const int L = (i / 3) * G + c; if (L >= 512) return false; pg8::swz_tile(L, 128, 4, u.pm, u.pn); u.k = i % 3; return true; }
;     DI bool next(int i, Unit& u) const { if (i >= 3) return false; u.pm = pm; u.pn = pn; u.k = i; return true; }
;     DI bool next(int i, Unit& u) const { if (i >= 1) return false; u.pm = pm; u.pn = pn; u.k = 0; return true; }
;     DI bool next(int i, Unit& u) const { if (i >= 1) return false; u.pm = pm; u.pn = pn; u.k = half; return true; }
;     DI bool next(int i, Unit& u) const { const int L = i * G + c; if (L >= nM * nN) return false; pg8::swz_tile(L, nM, nN, u.pm, u.pn); u.k = 0; return true; }
; template <class Epi, class Sched>
; DI void gemm_phase(LAS unsigned char* lds, const Sched& S, const Epi& E) {
;     ...
;     for (;;) {
;         const bool has_next = S.next(ui + 1, nxt);
;         const char* nA = has_next ? S.pa(nxt) : cA; const char* nB = has_next ? S.pb(nxt) : cB;
;         for (int t = 0; t < nt; t += 2) {
.Lup3_nozero:
	s_waitcnt vmcnt(0)
	.p2align	6

; #define PG8_STAGE(bufoff, gbase, voff) do { _Pragma("unroll") for (int _i = 0; _i < 2; ++_i) \
;         __builtin_amdgcn_global_load_lds((const unsigned*)((const char*)(gbase) + (voff)[_i]), (LAS unsigned*)(lds + (bufoff) + ldsw + _i * 8192), 16, 0, 0); } while (0)
; #define PG8_WAIT_V(n) asm volatile("s_waitcnt vmcnt(" #n ")" ::: "memory")
; #define PG8_BAR __builtin_amdgcn_s_barrier()
;     DI bool next(int i, Unit& u) const { const int L = (i / 3) * G + c; if (L >= 512) return false; pg8::swz_tile(L, 128, 4, u.pm, u.pn); u.k = i % 3; return true; }
;     DI bool next(int i, Unit& u) const { if (i >= 3) return false; u.pm = pm; u.pn = pn; u.k = i; return true; }
;     DI bool next(int i, Unit& u) const { if (i >= 1) return false; u.pm = pm; u.pn = pn; u.k = 0; return true; }
;     DI bool next(int i, Unit& u) const { if (i >= 1) return false; u.pm = pm; u.pn = pn; u.k = half; return true; }
; template <class Epi, class Sched>
; DI void gemm_phase(LAS unsigned char* lds, const Sched& S, const Epi& E) {
;     ...
;     for (int i = 0; i < 2; ++i) { int R, C; stage_rc(tid * 16 + i * 8192, R, C); const int Rb = (R & ~31) + perm32(R & 31);
;         voffA[i] = (unsigned)(R * lda + C) * 2u; voffB[i] = (unsigned)(Rb * ldb + C) * 2u; }
;     const size_t kstep = (size_t)(BK * 2);
;     const size_t hstepA = (size_t)HALF * lda * 2, hstepB = (size_t)HALF * ldb * 2;
;     const unsigned ldsw = (unsigned)wid * 1024u;
;     const int aoff = lds_byte(wr * 64 + fr, fq * 8), boff = lds_byte(wc * 32 + fr, fq * 8);
;     ...
;     Unit cur, nxt; int ui = 0;
;     if (!S.next(0, cur)) return;
;     f32x4 acc[2][2][4][2];
; #pragma unroll
;     for (int a = 0; a < 2; ++a)
; #pragma unroll
;         for (int b = 0; b < 2; ++b)
; #pragma unroll
;             for (int m = 0; m < 4; ++m)
; #pragma unroll
;                 for (int n = 0; n < 2; ++n) acc[a][b][m][n] = (f32x4){0.f, 0.f, 0.f, 0.f};
;     bf16x8 At[4][2], B0[2][2], B1[2][2];
;     const char* cA = S.pa(cur); const char* cB = S.pb(cur);
;     PG8_STAGE(PG8_SB(0, 0), cB, voffB); PG8_STAGE(PG8_SB(0, 1), cB + hstepB, voffB); PG8_STAGE(PG8_SA(0, 0), cA, voffA); PG8_STAGE(PG8_SA(0, 1), cA + hstepA, voffA);
;     if (wr == 1) PG8_BAR;
;     PG8_WAIT_V(2); PG8_BAR;
;     PG8_STAGE(PG8_SB(1, 0), cB + kstep, voffB); PG8_STAGE(PG8_SA(1, 0), cA + kstep, voffA); PG8_STAGE(PG8_SB(1, 1), cB + hstepB + kstep, voffB);
;     PG8_WAIT_V(6); PG8_BAR;
.LBB0_1059:
	v_bfe_u32 v142, v183, 4, 2
	s_lshl_b32 s8, s8, 5
	v_and_b32_e32 v143, 15, v183
	v_lshlrev_b32_e32 v14, 4, v142
	v_lshlrev_b32_e32 v15, 6, v183
	s_movk_i32 s11, 0x3c0
	v_lshlrev_b32_e32 v16, 2, v183
	s_and_b32 s24, s8, 0x60
	v_and_or_b32 v15, v15, s11, v14
	v_and_b32_e32 v16, 32, v16
	s_lshl_b32 s23, s9, 6
	v_lshl_or_b32 v14, v143, 6, v14
	s_lshl_b32 s9, s9, 13
	s_lshl_b32 s8, s24, 7
	v_bitop3_b32 v18, s8, v15, v16 bitop3:0xf6
	v_bitop3_b32 v19, v14, s9, v16 bitop3:0xde
	s_mov_b64 s[8:9], 0x80
	s_add_u32 s14, s4, 0x40080
	v_lshl_add_u64 v[2:3], v[2:3], 0, s[8:9]
	s_addc_u32 s15, s5, 0
	s_add_i32 m0, s19, 0x18000
	v_lshl_add_u64 v[4:5], v[4:5], 0, s[8:9]
	s_waitcnt vmcnt(2)
	s_barrier
	global_load_lds_dwordx4 v[2:3], off
	s_add_i32 m0, s19, 0x1a000
	s_add_i32 s25, s19, 0x8000
	v_lshl_add_u64 v[6:7], v[6:7], 0, s[8:9]
	global_load_lds_dwordx4 v[4:5], off
	s_mov_b32 m0, s25
	s_add_i32 s26, s19, 0xa000
	v_lshl_add_u64 v[8:9], v[8:9], 0, s[8:9]
	global_load_lds_dwordx4 v[6:7], off
	s_mov_b32 m0, s26
	v_lshl_add_u64 v[14:15], s[14:15], 0, v[132:133]
	global_load_lds_dwordx4 v[8:9], off
	s_add_i32 m0, s19, 0x1c000
	v_lshl_add_u64 v[16:17], s[14:15], 0, v[136:137]
	global_load_lds_dwordx4 v[14:15], off
	s_add_i32 m0, s19, 0x1e000
	s_mul_hi_i32 s11, s10, 0x320000
	global_load_lds_dwordx4 v[16:17], off
	s_mul_i32 s10, s10, 0x320000
	v_add_u16_e32 v2, v10, v11
	v_lshrrev_b16_e32 v4, 1, v2
	s_add_u32 s10, s48, s10
	s_waitcnt vmcnt(6)
	v_add_lshl_u32 v2, v12, v4, 1
	v_mov_b32_e32 v3, v133
	s_addc_u32 s11, s49, s11
	s_add_i32 s30, 0, 0x10000
	s_add_i32 s33, 0, 0x14000
	s_add_i32 s35, 0, 0x18000
	s_add_i32 s37, 0, 0x1c000
	v_lshl_add_u64 v[138:139], s[10:11], 0, v[2:3]
	v_add_lshl_u32 v2, v13, v4, 1
	v_add_u32_e32 v144, s30, v18
	v_add_u32_e32 v145, s33, v18
	s_add_i32 s30, s30, s12
	s_add_i32 s33, s33, s12
	v_add_u32_e32 v147, s35, v18
	v_add_u32_e32 v148, s37, v18
	s_add_i32 s35, s35, s12
	s_add_i32 s37, s37, s12
	v_lshl_add_u64 v[140:141], s[10:11], 0, v[2:3]
	s_mov_b32 s27, -2
	s_mov_b64 s[10:11], 0x19191a80
	v_add_u32_e32 v146, 0, v19
	s_add_i32 s28, s19, 0xc000
	s_add_i32 s29, s19, 0xe000
	s_add_i32 s31, s30, 0x2000
	s_add_i32 s34, s33, 0x2000
	s_add_i32 s36, s35, 0x2000
	s_add_i32 s38, s37, 0x2000
	v_mov_b32_e32 v2, v133
	v_mov_b32_e32 v4, v133
	v_mov_b32_e32 v5, v133
	v_mov_b32_e32 v6, v133
	v_mov_b32_e32 v7, v133
	v_mov_b32_e32 v8, v133
	v_mov_b32_e32 v9, v133
	v_mov_b32_e32 v14, v133
	v_mov_b32_e32 v15, v133
	v_mov_b32_e32 v16, v133
	v_mov_b32_e32 v17, v133
	v_mov_b32_e32 v22, v133
	v_mov_b32_e32 v23, v133
	v_mov_b32_e32 v24, v133
	v_mov_b32_e32 v25, v133
	v_mov_b32_e32 v30, v133
	v_mov_b32_e32 v31, v133
	v_mov_b32_e32 v32, v133
	v_mov_b32_e32 v33, v133
	v_mov_b32_e32 v38, v133
	v_mov_b32_e32 v39, v133
	v_mov_b32_e32 v40, v133
	v_mov_b32_e32 v41, v133
	v_mov_b32_e32 v46, v133
	v_mov_b32_e32 v47, v133
	v_mov_b32_e32 v48, v133
	v_mov_b32_e32 v49, v133
	v_mov_b32_e32 v54, v133
	v_mov_b32_e32 v55, v133
	v_mov_b32_e32 v56, v133
	v_mov_b32_e32 v57, v133
	v_mov_b32_e32 v10, v133
	v_mov_b32_e32 v11, v133
	v_mov_b32_e32 v12, v133
	v_mov_b32_e32 v13, v133
	v_mov_b32_e32 v18, v133
	v_mov_b32_e32 v19, v133
	v_mov_b32_e32 v20, v133
	v_mov_b32_e32 v21, v133
	v_mov_b32_e32 v26, v133
	v_mov_b32_e32 v27, v133
	v_mov_b32_e32 v28, v133
	v_mov_b32_e32 v29, v133
	v_mov_b32_e32 v34, v133
	v_mov_b32_e32 v35, v133
	v_mov_b32_e32 v36, v133
	v_mov_b32_e32 v37, v133
	v_mov_b32_e32 v42, v133
	v_mov_b32_e32 v43, v133
	v_mov_b32_e32 v44, v133
	v_mov_b32_e32 v45, v133
	v_mov_b32_e32 v50, v133
	v_mov_b32_e32 v51, v133
	v_mov_b32_e32 v52, v133
	v_mov_b32_e32 v53, v133
	v_mov_b32_e32 v58, v133
	v_mov_b32_e32 v59, v133
	v_mov_b32_e32 v60, v133
	v_mov_b32_e32 v61, v133
	v_mov_b32_e32 v62, v133
	v_mov_b32_e32 v63, v133
	v_mov_b32_e32 v64, v133
	v_mov_b32_e32 v65, v133
	v_mov_b32_e32 v66, v133
	v_mov_b32_e32 v67, v133
	v_mov_b32_e32 v68, v133
	v_mov_b32_e32 v69, v133
	v_mov_b32_e32 v70, v133
	v_mov_b32_e32 v71, v133
	v_mov_b32_e32 v72, v133
	v_mov_b32_e32 v73, v133
	v_mov_b32_e32 v78, v133
	v_mov_b32_e32 v79, v133
	v_mov_b32_e32 v80, v133
	v_mov_b32_e32 v81, v133
	v_mov_b32_e32 v86, v133
	v_mov_b32_e32 v87, v133
	v_mov_b32_e32 v88, v133
	v_mov_b32_e32 v89, v133
	v_mov_b32_e32 v94, v133
	v_mov_b32_e32 v95, v133
	v_mov_b32_e32 v96, v133
	v_mov_b32_e32 v97, v133
	v_mov_b32_e32 v102, v133
	v_mov_b32_e32 v103, v133
	v_mov_b32_e32 v104, v133
	v_mov_b32_e32 v105, v133
	v_mov_b32_e32 v110, v133
	v_mov_b32_e32 v111, v133
	v_mov_b32_e32 v112, v133
	v_mov_b32_e32 v113, v133
	v_mov_b32_e32 v118, v133
	v_mov_b32_e32 v119, v133
	v_mov_b32_e32 v120, v133
	v_mov_b32_e32 v121, v133
	v_mov_b32_e32 v74, v133
	v_mov_b32_e32 v75, v133
	v_mov_b32_e32 v76, v133
	v_mov_b32_e32 v77, v133
	v_mov_b32_e32 v82, v133
	v_mov_b32_e32 v83, v133
	v_mov_b32_e32 v84, v133
	v_mov_b32_e32 v85, v133
	v_mov_b32_e32 v90, v133
	v_mov_b32_e32 v91, v133
	v_mov_b32_e32 v92, v133
	v_mov_b32_e32 v93, v133
	v_mov_b32_e32 v98, v133
	v_mov_b32_e32 v99, v133
	v_mov_b32_e32 v100, v133
	v_mov_b32_e32 v101, v133
	v_mov_b32_e32 v106, v133
	v_mov_b32_e32 v107, v133
	v_mov_b32_e32 v108, v133
	v_mov_b32_e32 v109, v133
	v_mov_b32_e32 v114, v133
	v_mov_b32_e32 v115, v133
	v_mov_b32_e32 v116, v133
	v_mov_b32_e32 v117, v133
	v_mov_b32_e32 v122, v133
	v_mov_b32_e32 v123, v133
	v_mov_b32_e32 v124, v133
	v_mov_b32_e32 v125, v133
	v_mov_b32_e32 v126, v133
	v_mov_b32_e32 v127, v133
	v_mov_b32_e32 v128, v133
	v_mov_b32_e32 v129, v133
	s_barrier
	.p2align	6

;     DI bool next(int i, Unit& u) const { const int L = (i / 3) * G + c; if (L >= 512) return false; pg8::swz_tile(L, 128, 4, u.pm, u.pn); u.k = i % 3; return true; }
;     DI bool next(int i, Unit& u) const { if (i >= 3) return false; u.pm = pm; u.pn = pn; u.k = i; return true; }
;     DI bool next(int i, Unit& u) const { if (i >= 1) return false; u.pm = pm; u.pn = pn; u.k = 0; return true; }
;     DI bool next(int i, Unit& u) const { if (i >= 1) return false; u.pm = pm; u.pn = pn; u.k = half; return true; }
;     DI bool next(int i, Unit& u) const { const int L = i * G + c; if (L >= nM * nN) return false; pg8::swz_tile(L, nM, nN, u.pm, u.pn); u.k = 0; return true; }
; template <class Epi, class Sched>
; DI void gemm_phase(LAS unsigned char* lds, const Sched& S, const Epi& E) {
;     ...
;         const bool has_next = S.next(ui + 1, nxt);
;         const char* nA = has_next ? S.pa(nxt) : cA; const char* nB = has_next ? S.pb(nxt) : cB;
;     ...
; #pragma unroll
;         for (int a = 0; a < 2; ++a)
; #pragma unroll
;             for (int b = 0; b < 2; ++b)
; #pragma unroll
;                 for (int m = 0; m < 4; ++m)
; #pragma unroll
;                     for (int n = 0; n < 2; ++n) acc[a][b][m][n] = (f32x4){0.f, 0.f, 0.f, 0.f};
;         cur = nxt; cA = nA; cB = nB; ++ui;
.LBB0_1355:
	s_ashr_i32 s17, s16, 31
	s_lshl_b64 s[20:21], s[16:17], 19
	s_add_u32 s20, s64, s20
	s_addc_u32 s21, s65, s21
	s_and_b64 s[26:27], s[26:27], exec
	s_cselect_b32 s17, s21, s25
	s_cselect_b32 s51, s20, s24
	s_add_u32 s22, s22, 0x190080
	s_addc_u32 s23, s23, 0
	s_add_u32 s52, s24, 0x100
	v_mov_b32_e32 v2, 0
	s_addc_u32 s53, s25, 0
	s_mov_b32 s54, -2
	v_mov_b32_e32 v3, v2
	v_mov_b32_e32 v4, v2
	v_mov_b32_e32 v5, v2
	v_mov_b32_e32 v6, v2
	v_mov_b32_e32 v7, v2
	v_mov_b32_e32 v8, v2
	v_mov_b32_e32 v9, v2
	v_mov_b32_e32 v14, v2
	v_mov_b32_e32 v15, v2
	v_mov_b32_e32 v16, v2
	v_mov_b32_e32 v17, v2
	v_mov_b32_e32 v22, v2
	v_mov_b32_e32 v23, v2
	v_mov_b32_e32 v24, v2
	v_mov_b32_e32 v25, v2
	v_mov_b32_e32 v30, v2
	v_mov_b32_e32 v31, v2
	v_mov_b32_e32 v32, v2
	v_mov_b32_e32 v33, v2
	v_mov_b32_e32 v38, v2
	v_mov_b32_e32 v39, v2
	v_mov_b32_e32 v40, v2
	v_mov_b32_e32 v41, v2
	v_mov_b32_e32 v46, v2
	v_mov_b32_e32 v47, v2
	v_mov_b32_e32 v48, v2
	v_mov_b32_e32 v49, v2
	v_mov_b32_e32 v54, v2
	v_mov_b32_e32 v55, v2
	v_mov_b32_e32 v56, v2
	v_mov_b32_e32 v57, v2
	v_mov_b32_e32 v10, v2
	v_mov_b32_e32 v11, v2
	v_mov_b32_e32 v12, v2
	v_mov_b32_e32 v13, v2
	v_mov_b32_e32 v18, v2
	v_mov_b32_e32 v19, v2
	v_mov_b32_e32 v20, v2
	v_mov_b32_e32 v21, v2
	v_mov_b32_e32 v26, v2
	v_mov_b32_e32 v27, v2
	v_mov_b32_e32 v28, v2
	v_mov_b32_e32 v29, v2
	v_mov_b32_e32 v34, v2
	v_mov_b32_e32 v35, v2
	v_mov_b32_e32 v36, v2
	v_mov_b32_e32 v37, v2
	v_mov_b32_e32 v42, v2
	v_mov_b32_e32 v43, v2
	v_mov_b32_e32 v44, v2
	v_mov_b32_e32 v45, v2
	v_mov_b32_e32 v50, v2
	v_mov_b32_e32 v51, v2
	v_mov_b32_e32 v52, v2
	v_mov_b32_e32 v53, v2
	v_mov_b32_e32 v58, v2
	v_mov_b32_e32 v59, v2
	v_mov_b32_e32 v60, v2
	v_mov_b32_e32 v61, v2
	v_mov_b32_e32 v62, v2
	v_mov_b32_e32 v63, v2
	v_mov_b32_e32 v64, v2
	v_mov_b32_e32 v65, v2
	v_mov_b32_e32 v66, v2
	v_mov_b32_e32 v67, v2
	v_mov_b32_e32 v68, v2
	v_mov_b32_e32 v69, v2
	v_mov_b32_e32 v70, v2
	v_mov_b32_e32 v71, v2
	v_mov_b32_e32 v72, v2
	v_mov_b32_e32 v73, v2
	v_mov_b32_e32 v78, v2
	v_mov_b32_e32 v79, v2
	v_mov_b32_e32 v80, v2
	v_mov_b32_e32 v81, v2
	v_mov_b32_e32 v86, v2
	v_mov_b32_e32 v87, v2
	v_mov_b32_e32 v88, v2
	v_mov_b32_e32 v89, v2
	v_mov_b32_e32 v94, v2
	v_mov_b32_e32 v95, v2
	v_mov_b32_e32 v96, v2
	v_mov_b32_e32 v97, v2
	v_mov_b32_e32 v102, v2
	v_mov_b32_e32 v103, v2
	v_mov_b32_e32 v104, v2
	v_mov_b32_e32 v105, v2
	v_mov_b32_e32 v110, v2
	v_mov_b32_e32 v111, v2
	v_mov_b32_e32 v112, v2
	v_mov_b32_e32 v113, v2
	v_mov_b32_e32 v118, v2
	v_mov_b32_e32 v119, v2
	v_mov_b32_e32 v120, v2
	v_mov_b32_e32 v121, v2
	v_mov_b32_e32 v74, v2
	v_mov_b32_e32 v75, v2
	v_mov_b32_e32 v76, v2
	v_mov_b32_e32 v77, v2
	v_mov_b32_e32 v82, v2
	v_mov_b32_e32 v83, v2
	v_mov_b32_e32 v84, v2
	v_mov_b32_e32 v85, v2
	v_mov_b32_e32 v90, v2
	v_mov_b32_e32 v91, v2
	v_mov_b32_e32 v92, v2
	v_mov_b32_e32 v93, v2
	v_mov_b32_e32 v98, v2
	v_mov_b32_e32 v99, v2
	v_mov_b32_e32 v100, v2
	v_mov_b32_e32 v101, v2
	v_mov_b32_e32 v106, v2
	v_mov_b32_e32 v107, v2
	v_mov_b32_e32 v108, v2
	v_mov_b32_e32 v109, v2
	v_mov_b32_e32 v114, v2
	v_mov_b32_e32 v115, v2
	v_mov_b32_e32 v116, v2
	v_mov_b32_e32 v117, v2
	v_mov_b32_e32 v122, v2
	v_mov_b32_e32 v123, v2
	v_mov_b32_e32 v124, v2
	v_mov_b32_e32 v125, v2
	v_mov_b32_e32 v126, v2
	v_mov_b32_e32 v127, v2
	v_mov_b32_e32 v128, v2
	v_mov_b32_e32 v129, v2
	s_waitcnt vmcnt(0)
	.p2align	6

;     DI bool next(int i, Unit& u) const { const int L = (i / 3) * G + c; if (L >= 512) return false; pg8::swz_tile(L, 128, 4, u.pm, u.pn); u.k = i % 3; return true; }
;     DI bool next(int i, Unit& u) const { if (i >= 3) return false; u.pm = pm; u.pn = pn; u.k = i; return true; }
;     DI bool next(int i, Unit& u) const { if (i >= 1) return false; u.pm = pm; u.pn = pn; u.k = 0; return true; }
;     DI bool next(int i, Unit& u) const { if (i >= 1) return false; u.pm = pm; u.pn = pn; u.k = half; return true; }
;     DI bool next(int i, Unit& u) const { const int L = i * G + c; if (L >= nM * nN) return false; pg8::swz_tile(L, nM, nN, u.pm, u.pn); u.k = 0; return true; }
; template <class Epi, class Sched>
; DI void gemm_phase(LAS unsigned char* lds, const Sched& S, const Epi& E) {
;     ...
;         const bool has_next = S.next(ui + 1, nxt);
;         const char* nA = has_next ? S.pa(nxt) : cA; const char* nB = has_next ? S.pb(nxt) : cB;
;     ...
; #pragma unroll
;         for (int a = 0; a < 2; ++a)
; #pragma unroll
;             for (int b = 0; b < 2; ++b)
; #pragma unroll
;                 for (int m = 0; m < 4; ++m)
; #pragma unroll
;                     for (int n = 0; n < 2; ++n) acc[a][b][m][n] = (f32x4){0.f, 0.f, 0.f, 0.f};
;         cur = nxt; cA = nA; cB = nB; ++ui;
.LBB0_1514:
	s_ashr_i32 s17, s16, 31
	s_lshl_b64 s[20:21], s[16:17], 19
	s_add_u32 s20, s60, s20
	s_addc_u32 s21, s61, s21
	s_and_b64 s[26:27], s[26:27], exec
	s_cselect_b32 s17, s21, s25
	s_cselect_b32 s51, s20, s24
	s_add_u32 s22, s22, 0x190080
	s_addc_u32 s23, s23, 0
	s_add_u32 s52, s24, 0x100
	v_mov_b32_e32 v2, 0
	s_addc_u32 s53, s25, 0
	s_mov_b32 s54, -2
	v_mov_b32_e32 v3, v2
	v_mov_b32_e32 v4, v2
	v_mov_b32_e32 v5, v2
	v_mov_b32_e32 v6, v2
	v_mov_b32_e32 v7, v2
	v_mov_b32_e32 v8, v2
	v_mov_b32_e32 v9, v2
	v_mov_b32_e32 v18, v2
	v_mov_b32_e32 v19, v2
	v_mov_b32_e32 v20, v2
	v_mov_b32_e32 v21, v2
	v_mov_b32_e32 v22, v2
	v_mov_b32_e32 v23, v2
	v_mov_b32_e32 v24, v2
	v_mov_b32_e32 v25, v2
	v_mov_b32_e32 v34, v2
	v_mov_b32_e32 v35, v2
	v_mov_b32_e32 v36, v2
	v_mov_b32_e32 v37, v2
	v_mov_b32_e32 v38, v2
	v_mov_b32_e32 v39, v2
	v_mov_b32_e32 v40, v2
	v_mov_b32_e32 v41, v2
	v_mov_b32_e32 v50, v2
	v_mov_b32_e32 v51, v2
	v_mov_b32_e32 v52, v2
	v_mov_b32_e32 v53, v2
	v_mov_b32_e32 v54, v2
	v_mov_b32_e32 v55, v2
	v_mov_b32_e32 v56, v2
	v_mov_b32_e32 v57, v2
	v_mov_b32_e32 v10, v2
	v_mov_b32_e32 v11, v2
	v_mov_b32_e32 v12, v2
	v_mov_b32_e32 v13, v2
	v_mov_b32_e32 v14, v2
	v_mov_b32_e32 v15, v2
	v_mov_b32_e32 v16, v2
	v_mov_b32_e32 v17, v2
	v_mov_b32_e32 v26, v2
	v_mov_b32_e32 v27, v2
	v_mov_b32_e32 v28, v2
	v_mov_b32_e32 v29, v2
	v_mov_b32_e32 v30, v2
	v_mov_b32_e32 v31, v2
	v_mov_b32_e32 v32, v2
	v_mov_b32_e32 v33, v2
	v_mov_b32_e32 v42, v2
	v_mov_b32_e32 v43, v2
	v_mov_b32_e32 v44, v2
	v_mov_b32_e32 v45, v2
	v_mov_b32_e32 v46, v2
	v_mov_b32_e32 v47, v2
	v_mov_b32_e32 v48, v2
	v_mov_b32_e32 v49, v2
	v_mov_b32_e32 v58, v2
	v_mov_b32_e32 v59, v2
	v_mov_b32_e32 v60, v2
	v_mov_b32_e32 v61, v2
	v_mov_b32_e32 v62, v2
	v_mov_b32_e32 v63, v2
	v_mov_b32_e32 v64, v2
	v_mov_b32_e32 v65, v2
	v_mov_b32_e32 v66, v2
	v_mov_b32_e32 v67, v2
	v_mov_b32_e32 v68, v2
	v_mov_b32_e32 v69, v2
	v_mov_b32_e32 v70, v2
	v_mov_b32_e32 v71, v2
	v_mov_b32_e32 v72, v2
	v_mov_b32_e32 v73, v2
	v_mov_b32_e32 v82, v2
	v_mov_b32_e32 v83, v2
	v_mov_b32_e32 v84, v2
	v_mov_b32_e32 v85, v2
	v_mov_b32_e32 v86, v2
	v_mov_b32_e32 v87, v2
	v_mov_b32_e32 v88, v2
	v_mov_b32_e32 v89, v2
	v_mov_b32_e32 v98, v2
	v_mov_b32_e32 v99, v2
	v_mov_b32_e32 v100, v2
	v_mov_b32_e32 v101, v2
	v_mov_b32_e32 v102, v2
	v_mov_b32_e32 v103, v2
	v_mov_b32_e32 v104, v2
	v_mov_b32_e32 v105, v2
	v_mov_b32_e32 v114, v2
	v_mov_b32_e32 v115, v2
	v_mov_b32_e32 v116, v2
	v_mov_b32_e32 v117, v2
	v_mov_b32_e32 v118, v2
	v_mov_b32_e32 v119, v2
	v_mov_b32_e32 v120, v2
	v_mov_b32_e32 v121, v2
	v_mov_b32_e32 v74, v2
	v_mov_b32_e32 v75, v2
	v_mov_b32_e32 v76, v2
	v_mov_b32_e32 v77, v2
	v_mov_b32_e32 v78, v2
	v_mov_b32_e32 v79, v2
	v_mov_b32_e32 v80, v2
	v_mov_b32_e32 v81, v2
	v_mov_b32_e32 v90, v2
	v_mov_b32_e32 v91, v2
	v_mov_b32_e32 v92, v2
	v_mov_b32_e32 v93, v2
	v_mov_b32_e32 v94, v2
	v_mov_b32_e32 v95, v2
	v_mov_b32_e32 v96, v2
	v_mov_b32_e32 v97, v2
	v_mov_b32_e32 v106, v2
	v_mov_b32_e32 v107, v2
	v_mov_b32_e32 v108, v2
	v_mov_b32_e32 v109, v2
	v_mov_b32_e32 v110, v2
	v_mov_b32_e32 v111, v2
	v_mov_b32_e32 v112, v2
	v_mov_b32_e32 v113, v2
	v_mov_b32_e32 v122, v2
	v_mov_b32_e32 v123, v2
	v_mov_b32_e32 v124, v2
	v_mov_b32_e32 v125, v2
	v_mov_b32_e32 v126, v2
	v_mov_b32_e32 v127, v2
	v_mov_b32_e32 v128, v2
	v_mov_b32_e32 v129, v2
	.p2align	6

;     DI bool next(int i, Unit& u) const { const int L = (i / 3) * G + c; if (L >= 512) return false; pg8::swz_tile(L, 128, 4, u.pm, u.pn); u.k = i % 3; return true; }
;     DI bool next(int i, Unit& u) const { if (i >= 3) return false; u.pm = pm; u.pn = pn; u.k = i; return true; }
;     DI bool next(int i, Unit& u) const { if (i >= 1) return false; u.pm = pm; u.pn = pn; u.k = 0; return true; }
;     DI bool next(int i, Unit& u) const { if (i >= 1) return false; u.pm = pm; u.pn = pn; u.k = half; return true; }
;     DI bool next(int i, Unit& u) const { const int L = i * G + c; if (L >= nM * nN) return false; pg8::swz_tile(L, nM, nN, u.pm, u.pn); u.k = 0; return true; }
; template <class Epi, class Sched>
; DI void gemm_phase(LAS unsigned char* lds, const Sched& S, const Epi& E) {
;     ...
;         const bool has_next = S.next(ui + 1, nxt);
;         const char* nA = has_next ? S.pa(nxt) : cA; const char* nB = has_next ? S.pb(nxt) : cB;
;     ...
; #pragma unroll
;         for (int a = 0; a < 2; ++a)
; #pragma unroll
;             for (int b = 0; b < 2; ++b)
; #pragma unroll
;                 for (int m = 0; m < 4; ++m)
; #pragma unroll
;                     for (int n = 0; n < 2; ++n) acc[a][b][m][n] = (f32x4){0.f, 0.f, 0.f, 0.f};
;         cur = nxt; cA = nA; cB = nB; ++ui;
.LBB0_1607:
	s_add_u32 s20, s20, 0x190080
	s_addc_u32 s21, s21, 0
	s_add_u32 s54, s22, 0x100
	v_mov_b32_e32 v2, 0
	s_addc_u32 s55, s23, 0
	s_mov_b32 s58, -2
	v_mov_b32_e32 v3, v2
	v_mov_b32_e32 v4, v2
	v_mov_b32_e32 v5, v2
	v_mov_b32_e32 v6, v2
	v_mov_b32_e32 v7, v2
	v_mov_b32_e32 v8, v2
	v_mov_b32_e32 v9, v2
	v_mov_b32_e32 v14, v2
	v_mov_b32_e32 v15, v2
	v_mov_b32_e32 v16, v2
	v_mov_b32_e32 v17, v2
	v_mov_b32_e32 v22, v2
	v_mov_b32_e32 v23, v2
	v_mov_b32_e32 v24, v2
	v_mov_b32_e32 v25, v2
	v_mov_b32_e32 v30, v2
	v_mov_b32_e32 v31, v2
	v_mov_b32_e32 v32, v2
	v_mov_b32_e32 v33, v2
	v_mov_b32_e32 v38, v2
	v_mov_b32_e32 v39, v2
	v_mov_b32_e32 v40, v2
	v_mov_b32_e32 v41, v2
	v_mov_b32_e32 v46, v2
	v_mov_b32_e32 v47, v2
	v_mov_b32_e32 v48, v2
	v_mov_b32_e32 v49, v2
	v_mov_b32_e32 v54, v2
	v_mov_b32_e32 v55, v2
	v_mov_b32_e32 v56, v2
	v_mov_b32_e32 v57, v2
	v_mov_b32_e32 v10, v2
	v_mov_b32_e32 v11, v2
	v_mov_b32_e32 v12, v2
	v_mov_b32_e32 v13, v2
	v_mov_b32_e32 v18, v2
	v_mov_b32_e32 v19, v2
	v_mov_b32_e32 v20, v2
	v_mov_b32_e32 v21, v2
	v_mov_b32_e32 v26, v2
	v_mov_b32_e32 v27, v2
	v_mov_b32_e32 v28, v2
	v_mov_b32_e32 v29, v2
	v_mov_b32_e32 v34, v2
	v_mov_b32_e32 v35, v2
	v_mov_b32_e32 v36, v2
	v_mov_b32_e32 v37, v2
	v_mov_b32_e32 v42, v2
	v_mov_b32_e32 v43, v2
	v_mov_b32_e32 v44, v2
	v_mov_b32_e32 v45, v2
	v_mov_b32_e32 v50, v2
	v_mov_b32_e32 v51, v2
	v_mov_b32_e32 v52, v2
	v_mov_b32_e32 v53, v2
	v_mov_b32_e32 v58, v2
	v_mov_b32_e32 v59, v2
	v_mov_b32_e32 v60, v2
	v_mov_b32_e32 v61, v2
	v_mov_b32_e32 v62, v2
	v_mov_b32_e32 v63, v2
	v_mov_b32_e32 v64, v2
	v_mov_b32_e32 v65, v2
	v_mov_b32_e32 v66, v2
	v_mov_b32_e32 v67, v2
	v_mov_b32_e32 v68, v2
	v_mov_b32_e32 v69, v2
	v_mov_b32_e32 v70, v2
	v_mov_b32_e32 v71, v2
	v_mov_b32_e32 v72, v2
	v_mov_b32_e32 v73, v2
	v_mov_b32_e32 v78, v2
	v_mov_b32_e32 v79, v2
	v_mov_b32_e32 v80, v2
	v_mov_b32_e32 v81, v2
	v_mov_b32_e32 v86, v2
	v_mov_b32_e32 v87, v2
	v_mov_b32_e32 v88, v2
	v_mov_b32_e32 v89, v2
	v_mov_b32_e32 v94, v2
	v_mov_b32_e32 v95, v2
	v_mov_b32_e32 v96, v2
	v_mov_b32_e32 v97, v2
	v_mov_b32_e32 v102, v2
	v_mov_b32_e32 v103, v2
	v_mov_b32_e32 v104, v2
	v_mov_b32_e32 v105, v2
	v_mov_b32_e32 v110, v2
	v_mov_b32_e32 v111, v2
	v_mov_b32_e32 v112, v2
	v_mov_b32_e32 v113, v2
	v_mov_b32_e32 v114, v2
	v_mov_b32_e32 v115, v2
	v_mov_b32_e32 v116, v2
	v_mov_b32_e32 v117, v2
	v_mov_b32_e32 v74, v2
	v_mov_b32_e32 v75, v2
	v_mov_b32_e32 v76, v2
	v_mov_b32_e32 v77, v2
	v_mov_b32_e32 v82, v2
	v_mov_b32_e32 v83, v2
	v_mov_b32_e32 v84, v2
	v_mov_b32_e32 v85, v2
	v_mov_b32_e32 v90, v2
	v_mov_b32_e32 v91, v2
	v_mov_b32_e32 v92, v2
	v_mov_b32_e32 v93, v2
	v_mov_b32_e32 v98, v2
	v_mov_b32_e32 v99, v2
	v_mov_b32_e32 v100, v2
	v_mov_b32_e32 v101, v2
	v_mov_b32_e32 v106, v2
	v_mov_b32_e32 v107, v2
	v_mov_b32_e32 v108, v2
	v_mov_b32_e32 v109, v2
	v_mov_b32_e32 v118, v2
	v_mov_b32_e32 v119, v2
	v_mov_b32_e32 v120, v2
	v_mov_b32_e32 v121, v2
	v_mov_b32_e32 v122, v2
	v_mov_b32_e32 v123, v2
	v_mov_b32_e32 v124, v2
	v_mov_b32_e32 v125, v2
	v_mov_b32_e32 v126, v2
	v_mov_b32_e32 v127, v2
	v_mov_b32_e32 v128, v2
	v_mov_b32_e32 v129, v2
	s_waitcnt vmcnt(0)
	.p2align	6

; #define PG8_STAGE(bufoff, gbase, voff) do { _Pragma("unroll") for (int _i = 0; _i < 2; ++_i) \
;         __builtin_amdgcn_global_load_lds((const unsigned*)((const char*)(gbase) + (voff)[_i]), (LAS unsigned*)(lds + (bufoff) + ldsw + _i * 8192), 16, 0, 0); } while (0)
; #define PG8_WAIT_V(n) asm volatile("s_waitcnt vmcnt(" #n ")" ::: "memory")
; #define PG8_BAR __builtin_amdgcn_s_barrier()
;     DI bool next(int i, Unit& u) const { const int L = (i / 3) * G + c; if (L >= 512) return false; pg8::swz_tile(L, 128, 4, u.pm, u.pn); u.k = i % 3; return true; }
;     DI bool next(int i, Unit& u) const { if (i >= 3) return false; u.pm = pm; u.pn = pn; u.k = i; return true; }
;     DI bool next(int i, Unit& u) const { if (i >= 1) return false; u.pm = pm; u.pn = pn; u.k = 0; return true; }
;     DI bool next(int i, Unit& u) const { if (i >= 1) return false; u.pm = pm; u.pn = pn; u.k = half; return true; }
; template <class Epi, class Sched>
; DI void gemm_phase(LAS unsigned char* lds, const Sched& S, const Epi& E) {
;     ...
;     for (int i = 0; i < 2; ++i) { int R, C; stage_rc(tid * 16 + i * 8192, R, C); const int Rb = (R & ~31) + perm32(R & 31);
;         voffA[i] = (unsigned)(R * lda + C) * 2u; voffB[i] = (unsigned)(Rb * ldb + C) * 2u; }
;     const size_t kstep = (size_t)(BK * 2);
;     const size_t hstepA = (size_t)HALF * lda * 2, hstepB = (size_t)HALF * ldb * 2;
;     const unsigned ldsw = (unsigned)wid * 1024u;
;     const int aoff = lds_byte(wr * 64 + fr, fq * 8), boff = lds_byte(wc * 32 + fr, fq * 8);
;     ...
;     Unit cur, nxt; int ui = 0;
;     if (!S.next(0, cur)) return;
;     f32x4 acc[2][2][4][2];
; #pragma unroll
;     for (int a = 0; a < 2; ++a)
; #pragma unroll
;         for (int b = 0; b < 2; ++b)
; #pragma unroll
;             for (int m = 0; m < 4; ++m)
; #pragma unroll
;                 for (int n = 0; n < 2; ++n) acc[a][b][m][n] = (f32x4){0.f, 0.f, 0.f, 0.f};
;     bf16x8 At[4][2], B0[2][2], B1[2][2];
;     const char* cA = S.pa(cur); const char* cB = S.pb(cur);
;     PG8_STAGE(PG8_SB(0, 0), cB, voffB); PG8_STAGE(PG8_SB(0, 1), cB + hstepB, voffB); PG8_STAGE(PG8_SA(0, 0), cA, voffA); PG8_STAGE(PG8_SA(0, 1), cA + hstepA, voffA);
;     if (wr == 1) PG8_BAR;
;     PG8_WAIT_V(2); PG8_BAR;
;     PG8_STAGE(PG8_SB(1, 0), cB + kstep, voffB); PG8_STAGE(PG8_SA(1, 0), cA + kstep, voffA); PG8_STAGE(PG8_SB(1, 1), cB + hstepB + kstep, voffB);
;     PG8_WAIT_V(6); PG8_BAR;
.LBB0_1694:
	v_bfe_u32 v1, v183, 4, 2
	s_lshl_b32 s9, s9, 5
	v_and_b32_e32 v138, 15, v183
	v_lshlrev_b32_e32 v14, 4, v1
	v_lshlrev_b32_e32 v15, 6, v183
	s_movk_i32 s12, 0x3c0
	v_lshlrev_b32_e32 v16, 2, v183
	s_and_b32 s28, s9, 0x60
	v_and_or_b32 v15, v15, s12, v14
	v_and_b32_e32 v16, 32, v16
	s_lshl_b32 s12, s14, 6
	v_lshl_or_b32 v14, v138, 6, v14
	s_lshl_b32 s14, s14, 13
	s_lshl_b32 s9, s28, 7
	v_bitop3_b32 v18, v14, s14, v16 bitop3:0xde
	s_mov_b64 s[14:15], 0x80
	s_add_u32 s20, s2, 0xb0080
	v_lshl_add_u64 v[2:3], v[2:3], 0, s[14:15]
	s_addc_u32 s21, s3, 0
	s_add_i32 m0, s26, 0x18000
	v_lshl_add_u64 v[4:5], v[4:5], 0, s[14:15]
	s_waitcnt vmcnt(2)
	s_barrier
	global_load_lds_dwordx4 v[2:3], off
	s_add_i32 m0, s26, 0x1a000
	s_add_i32 s31, s26, 0x8000
	v_lshl_add_u64 v[6:7], v[6:7], 0, s[14:15]
	global_load_lds_dwordx4 v[4:5], off
	s_mov_b32 m0, s31
	s_add_i32 s33, s26, 0xa000
	v_lshl_add_u64 v[8:9], v[8:9], 0, s[14:15]
	global_load_lds_dwordx4 v[6:7], off
	s_mov_b32 m0, s33
	v_bitop3_b32 v19, s9, v15, v16 bitop3:0xf6
	v_lshl_add_u64 v[14:15], s[20:21], 0, v[132:133]
	global_load_lds_dwordx4 v[8:9], off
	s_add_i32 m0, s26, 0x1c000
	v_lshl_add_u64 v[16:17], s[20:21], 0, v[136:137]
	global_load_lds_dwordx4 v[14:15], off
	s_add_i32 m0, s26, 0x1e000
	s_mul_hi_i32 s21, s8, 0x320000
	global_load_lds_dwordx4 v[16:17], off
	s_mul_i32 s20, s8, 0x320000
	s_ashr_i32 s9, s8, 31
	s_or_b64 s[16:17], s[20:21], s[16:17]
	v_add_u16_e32 v2, v10, v11
	v_lshrrev_b16_e32 v4, 1, v2
	s_add_u32 s16, s48, s16
	v_add_lshl_u32 v2, v12, v4, 1
	v_mov_b32_e32 v3, v133
	s_addc_u32 s17, s49, s17
	v_lshl_add_u64 v[2:3], s[16:17], 0, v[2:3]
	s_mov_b64 s[20:21], 0x19191080
	s_waitcnt vmcnt(6)
	v_lshl_add_u64 v[140:141], v[2:3], 0, s[20:21]
	v_add_lshl_u32 v2, v13, v4, 1
	v_mov_b32_e32 v3, v133
	s_add_i32 s37, 0, 0x10000
	s_add_i32 s39, 0, 0x14000
	s_add_i32 s41, 0, 0x18000
	s_add_i32 s47, 0, 0x1c000
	v_lshl_add_u64 v[2:3], s[16:17], 0, v[2:3]
	v_add_u32_e32 v139, s37, v19
	v_add_u32_e32 v144, s39, v19
	s_add_i32 s37, s37, s18
	s_add_i32 s39, s39, s18
	v_add_u32_e32 v146, s41, v19
	v_add_u32_e32 v147, s47, v19
	s_add_i32 s41, s41, s18
	s_add_i32 s47, s47, s18
	v_lshl_add_u64 v[142:143], v[2:3], 0, s[20:21]
	s_mov_b32 s34, -2
	s_mov_b64 s[16:17], 0
	v_add_u32_e32 v145, 0, v18
	s_add_i32 s35, s26, 0xc000
	s_add_i32 s36, s26, 0xe000
	s_add_i32 s38, s37, 0x2000
	s_add_i32 s40, s39, 0x2000
	s_add_i32 s45, s41, 0x2000
	s_add_i32 s50, s47, 0x2000
	v_mov_b32_e32 v2, v133
	v_mov_b32_e32 v3, v133
	v_mov_b32_e32 v4, v133
	v_mov_b32_e32 v5, v133
	v_mov_b32_e32 v6, v133
	v_mov_b32_e32 v7, v133
	v_mov_b32_e32 v8, v133
	v_mov_b32_e32 v9, v133
	v_mov_b32_e32 v10, v133
	v_mov_b32_e32 v11, v133
	v_mov_b32_e32 v12, v133
	v_mov_b32_e32 v13, v133
	v_mov_b32_e32 v14, v133
	v_mov_b32_e32 v15, v133
	v_mov_b32_e32 v16, v133
	v_mov_b32_e32 v17, v133
	v_mov_b32_e32 v22, v133
	v_mov_b32_e32 v23, v133
	v_mov_b32_e32 v24, v133
	v_mov_b32_e32 v25, v133
	v_mov_b32_e32 v30, v133
	v_mov_b32_e32 v31, v133
	v_mov_b32_e32 v32, v133
	v_mov_b32_e32 v33, v133
	v_mov_b32_e32 v38, v133
	v_mov_b32_e32 v39, v133
	v_mov_b32_e32 v40, v133
	v_mov_b32_e32 v41, v133
	v_mov_b32_e32 v46, v133
	v_mov_b32_e32 v47, v133
	v_mov_b32_e32 v48, v133
	v_mov_b32_e32 v49, v133
	v_mov_b32_e32 v18, v133
	v_mov_b32_e32 v19, v133
	v_mov_b32_e32 v20, v133
	v_mov_b32_e32 v21, v133
	v_mov_b32_e32 v26, v133
	v_mov_b32_e32 v27, v133
	v_mov_b32_e32 v28, v133
	v_mov_b32_e32 v29, v133
	v_mov_b32_e32 v34, v133
	v_mov_b32_e32 v35, v133
	v_mov_b32_e32 v36, v133
	v_mov_b32_e32 v37, v133
	v_mov_b32_e32 v42, v133
	v_mov_b32_e32 v43, v133
	v_mov_b32_e32 v44, v133
	v_mov_b32_e32 v45, v133
	v_mov_b32_e32 v50, v133
	v_mov_b32_e32 v51, v133
	v_mov_b32_e32 v52, v133
	v_mov_b32_e32 v53, v133
	v_mov_b32_e32 v54, v133
	v_mov_b32_e32 v55, v133
	v_mov_b32_e32 v56, v133
	v_mov_b32_e32 v57, v133
	v_mov_b32_e32 v58, v133
	v_mov_b32_e32 v59, v133
	v_mov_b32_e32 v60, v133
	v_mov_b32_e32 v61, v133
	v_mov_b32_e32 v62, v133
	v_mov_b32_e32 v63, v133
	v_mov_b32_e32 v64, v133
	v_mov_b32_e32 v65, v133
	v_mov_b32_e32 v66, v133
	v_mov_b32_e32 v67, v133
	v_mov_b32_e32 v68, v133
	v_mov_b32_e32 v69, v133
	v_mov_b32_e32 v70, v133
	v_mov_b32_e32 v71, v133
	v_mov_b32_e32 v72, v133
	v_mov_b32_e32 v73, v133
	v_mov_b32_e32 v74, v133
	v_mov_b32_e32 v75, v133
	v_mov_b32_e32 v76, v133
	v_mov_b32_e32 v77, v133
	v_mov_b32_e32 v78, v133
	v_mov_b32_e32 v79, v133
	v_mov_b32_e32 v80, v133
	v_mov_b32_e32 v81, v133
	v_mov_b32_e32 v86, v133
	v_mov_b32_e32 v87, v133
	v_mov_b32_e32 v88, v133
	v_mov_b32_e32 v89, v133
	v_mov_b32_e32 v94, v133
	v_mov_b32_e32 v95, v133
	v_mov_b32_e32 v96, v133
	v_mov_b32_e32 v97, v133
	v_mov_b32_e32 v102, v133
	v_mov_b32_e32 v103, v133
	v_mov_b32_e32 v104, v133
	v_mov_b32_e32 v105, v133
	v_mov_b32_e32 v110, v133
	v_mov_b32_e32 v111, v133
	v_mov_b32_e32 v112, v133
	v_mov_b32_e32 v113, v133
	v_mov_b32_e32 v82, v133
	v_mov_b32_e32 v83, v133
	v_mov_b32_e32 v84, v133
	v_mov_b32_e32 v85, v133
	v_mov_b32_e32 v90, v133
	v_mov_b32_e32 v91, v133
	v_mov_b32_e32 v92, v133
	v_mov_b32_e32 v93, v133
	v_mov_b32_e32 v98, v133
	v_mov_b32_e32 v99, v133
	v_mov_b32_e32 v100, v133
	v_mov_b32_e32 v101, v133
	v_mov_b32_e32 v106, v133
	v_mov_b32_e32 v107, v133
	v_mov_b32_e32 v108, v133
	v_mov_b32_e32 v109, v133
	v_mov_b32_e32 v114, v133
	v_mov_b32_e32 v115, v133
	v_mov_b32_e32 v116, v133
	v_mov_b32_e32 v117, v133
	v_mov_b32_e32 v118, v133
	v_mov_b32_e32 v119, v133
	v_mov_b32_e32 v120, v133
	v_mov_b32_e32 v121, v133
	v_mov_b32_e32 v122, v133
	v_mov_b32_e32 v123, v133
	v_mov_b32_e32 v124, v133
	v_mov_b32_e32 v125, v133
	v_mov_b32_e32 v126, v133
	v_mov_b32_e32 v127, v133
	v_mov_b32_e32 v128, v133
	v_mov_b32_e32 v129, v133
	s_barrier
	.p2align	6
